# out phase epilogue: residual-row pointer fetched once per tile and selected per lane (was a kernarg vector load + full drain per row, 16 per tile); residual loads of all rows in flight together
# speedup vs baseline: 1.0512x; 1.0090x over previous
; DI void out_phase(const Params& p, int l, char* smem, const bool dry = false) {
;     ...
;     float xo[4][4][4];
; #pragma unroll
;     for (int i = 0; i < 4; i++)
; #pragma unroll
;       for (int r = 0; r < 4; r++) {
;         const int tok = mt * 128 + wm * 64 + i * 16 + g4 * 4 + r;
;         const float* xr = xrow_ptr(p, l, tok);
; #pragma unroll
;         for (int jn = 0; jn < 4; jn++) xo[i][r][jn] = xr[nt * 128 + wn * 64 + jn * 16 + cl];
;       }
; #pragma unroll
;     for (int i = 0; i < 4; i++)
; #pragma unroll
;       for (int r = 0; r < 4; r++) {
;         const int tok = mt * 128 + wm * 64 + i * 16 + g4 * 4 + r;
; #pragma unroll
;         for (int jn = 0; jn < 4; jn++) {
;           const int n = nt * 128 + wn * 64 + jn * 16 + cl;
;           p.out[(size_t)tok * DM + n] = xo[i][r][jn] + acc[i][jn][r];
;         }
;       }
.LBB0_1737:
	v_cmp_eq_u32_e64 s[98:99], s58, v104
	v_cmp_eq_u32_e64 s[100:101], s86, v104
	s_nop 1
	v_cndmask_b32_e64 v104, v224, v222, s[100:101]
	v_cndmask_b32_e64 v105, v225, v223, s[100:101]
	v_cndmask_b32_e64 v104, v104, v220, s[98:99]
	v_cndmask_b32_e64 v105, v105, v221, s[98:99]
	s_waitcnt vmcnt(0)
	s_load_dwordx2 s[4:5], s[0:1], 0xe8
	v_lshlrev_b64 v[102:103], 12, v[102:103]
	v_add_f32_e32 v111, v52, v111
	v_add_f32_e32 v110, v56, v110
	v_add_f32_e32 v60, v60, v109
	v_add_f32_e32 v64, v64, v108
	v_add_f32_e32 v108, v53, v115
	v_add_f32_e32 v109, v57, v114
	v_lshlrev_b64 v[52:53], 12, v[74:75]
	v_add_f32_e32 v75, v58, v118
	v_lshlrev_b64 v[56:57], 12, v[76:77]
	v_add_f32_e32 v77, v59, v122
	v_lshlrev_b64 v[58:59], 12, v[80:81]
	v_lshlrev_b64 v[72:73], 2, v[72:73]
	v_add_f32_e32 v74, v54, v119
	v_add_f32_e32 v76, v55, v123
	v_lshlrev_b64 v[54:55], 12, v[78:79]
	v_add_f32_e32 v78, v48, v127
	v_add_f32_e32 v80, v49, v131
	s_waitcnt lgkmcnt(0)
	v_lshl_add_u64 v[48:49], s[4:5], 0, v[52:53]
	v_lshl_add_u64 v[52:53], s[4:5], 0, v[56:57]
	v_lshl_add_u64 v[56:57], s[4:5], 0, v[58:59]
	v_lshlrev_b64 v[68:69], 12, v[68:69]
	v_lshlrev_b64 v[70:71], 12, v[70:71]
	v_add_f32_e32 v65, v65, v112
	v_add_f32_e32 v79, v44, v126
	v_add_f32_e32 v112, v40, v125
	v_add_f32_e32 v81, v45, v130
	v_add_f32_e32 v114, v41, v129
	v_lshl_add_u64 v[40:41], s[4:5], 0, v[68:69]
	v_lshl_add_u64 v[44:45], s[4:5], 0, v[70:71]
	v_add_f32_e32 v61, v61, v113
	v_add_f32_e32 v113, v36, v124
	v_add_f32_e32 v115, v37, v128
	v_lshlrev_b64 v[36:37], 12, v[82:83]
	v_lshl_add_u64 v[54:55], s[4:5], 0, v[54:55]
	v_lshl_add_u64 v[36:37], s[4:5], 0, v[36:37]
	v_lshl_add_u64 v[40:41], v[40:41], 0, v[72:73]
	v_add_f32_e32 v62, v62, v117
	v_add_f32_e32 v66, v66, v116
	v_add_f32_e32 v63, v63, v121
	v_add_f32_e32 v67, v67, v120
	v_add_f32_e32 v50, v50, v135
	v_add_f32_e32 v46, v46, v134
	v_lshl_add_u64 v[44:45], v[44:45], 0, v[72:73]
	v_lshl_add_u64 v[48:49], v[48:49], 0, v[72:73]
	v_lshl_add_u64 v[52:53], v[52:53], 0, v[72:73]
	v_lshl_add_u64 v[54:55], v[54:55], 0, v[72:73]
	v_lshl_add_u64 v[56:57], v[56:57], 0, v[72:73]
	v_lshl_add_u64 v[36:37], v[36:37], 0, v[72:73]
	v_add_f32_e32 v38, v38, v132
	v_add_f32_e32 v16, v16, v143
	v_add_f32_e32 v12, v12, v142
	v_add_f32_e32 v8, v8, v141
	v_add_f32_e32 v4, v4, v140
	v_add_f32_e32 v6, v6, v148
	s_waitcnt vmcnt(0)
	v_lshl_add_u64 v[58:59], v[104:105], 0, v[102:103]
	v_lshl_add_u64 v[58:59], v[58:59], 0, v[72:73]
	global_load_dword v68, v[58:59], off
	global_load_dword v69, v[58:59], off offset:64
	global_load_dword v70, v[58:59], off offset:128
	s_nop 0
	global_load_dword v58, v[58:59], off offset:192
	s_nop 0
	global_store_dword v[40:41], v111, off
	global_store_dword v[40:41], v110, off offset:64
	global_store_dword v[40:41], v60, off offset:128
	global_store_dword v[40:41], v64, off offset:192
	global_store_dword v[44:45], v108, off
	global_store_dword v[44:45], v109, off offset:64
	global_store_dword v[44:45], v61, off offset:128
	global_store_dword v[44:45], v65, off offset:192
	global_store_dword v[48:49], v74, off
	global_store_dword v[48:49], v75, off offset:64
	global_store_dword v[48:49], v62, off offset:128
	global_store_dword v[48:49], v66, off offset:192
	global_store_dword v[52:53], v76, off
	global_store_dword v[52:53], v77, off offset:64
	global_store_dword v[52:53], v63, off offset:128
	global_store_dword v[52:53], v67, off offset:192
	global_store_dword v[54:55], v78, off
	global_store_dword v[54:55], v79, off offset:64
	global_store_dword v[54:55], v112, off offset:128
	global_store_dword v[54:55], v113, off offset:192
	global_store_dword v[56:57], v80, off
	global_store_dword v[56:57], v81, off offset:64
	global_store_dword v[56:57], v114, off offset:128
	global_store_dword v[56:57], v115, off offset:192
	global_store_dword v[36:37], v50, off
	global_store_dword v[36:37], v46, off offset:64
	v_add_f32_e32 v40, v42, v133
	global_store_dword v[36:37], v40, off offset:128
	global_store_dword v[36:37], v38, off offset:192
	v_lshlrev_b64 v[36:37], 12, v[84:85]
	v_lshl_add_u64 v[36:37], s[4:5], 0, v[36:37]
	v_add_f32_e32 v38, v51, v139
	v_lshl_add_u64 v[36:37], v[36:37], 0, v[72:73]
	global_store_dword v[36:37], v38, off
	v_add_f32_e32 v38, v47, v138
	global_store_dword v[36:37], v38, off offset:64
	v_add_f32_e32 v38, v43, v137
	global_store_dword v[36:37], v38, off offset:128
	v_add_f32_e32 v38, v39, v136
	global_store_dword v[36:37], v38, off offset:192
	v_lshlrev_b64 v[36:37], 12, v[86:87]
	v_lshl_add_u64 v[36:37], s[4:5], 0, v[36:37]
	v_lshl_add_u64 v[36:37], v[36:37], 0, v[72:73]
	global_store_dword v[36:37], v16, off
	global_store_dword v[36:37], v12, off offset:64
	global_store_dword v[36:37], v8, off offset:128
	global_store_dword v[36:37], v4, off offset:192
	v_lshlrev_b64 v[36:37], 12, v[88:89]
	v_lshl_add_u64 v[36:37], s[4:5], 0, v[36:37]
	v_add_f32_e32 v4, v17, v147
	v_lshl_add_u64 v[16:17], v[36:37], 0, v[72:73]
	global_store_dword v[16:17], v4, off
	v_add_f32_e32 v4, v13, v146
	global_store_dword v[16:17], v4, off offset:64
	v_add_f32_e32 v4, v9, v145
	global_store_dword v[16:17], v4, off offset:128
	v_add_f32_e32 v4, v5, v144
	global_store_dword v[16:17], v4, off offset:192
	v_lshlrev_b64 v[4:5], 12, v[90:91]
	v_lshl_add_u64 v[4:5], s[4:5], 0, v[4:5]
	v_add_f32_e32 v8, v18, v151
	v_lshl_add_u64 v[4:5], v[4:5], 0, v[72:73]
	global_store_dword v[4:5], v8, off
	v_add_f32_e32 v8, v14, v150
	global_store_dword v[4:5], v8, off offset:64
	v_add_f32_e32 v8, v10, v149
	global_store_dword v[4:5], v8, off offset:128
	global_store_dword v[4:5], v6, off offset:192
	v_lshlrev_b64 v[4:5], 12, v[92:93]
	v_lshl_add_u64 v[4:5], s[4:5], 0, v[4:5]
; DI void out_phase(const Params& p, int l, char* smem, const bool dry = false) {
;     ...
;   for (int e = slot;; e += slots) {
;     int mt, nt;
;     if (!xcd_tile(e, 8, mt, nt)) break;
;     ...
;     for (int i = 0; i < 4; i++)
; #pragma unroll
;       for (int r = 0; r < 4; r++) {
;         const int tok = mt * 128 + wm * 64 + i * 16 + g4 * 4 + r;
; #pragma unroll
;         for (int jn = 0; jn < 4; jn++) {
;           const int n = nt * 128 + wn * 64 + jn * 16 + cl;
;           p.out[(size_t)tok * DM + n] = xo[i][r][jn] + acc[i][jn][r];
;         }
;       }
	v_add_f32_e32 v6, v19, v155
	v_lshl_add_u64 v[4:5], v[4:5], 0, v[72:73]
	global_store_dword v[4:5], v6, off
	v_add_f32_e32 v6, v15, v154
	global_store_dword v[4:5], v6, off offset:64
	v_add_f32_e32 v6, v11, v153
	global_store_dword v[4:5], v6, off offset:128
	v_add_f32_e32 v6, v7, v152
	global_store_dword v[4:5], v6, off offset:192
	v_lshlrev_b64 v[4:5], 12, v[94:95]
	v_lshl_add_u64 v[4:5], s[4:5], 0, v[4:5]
	v_add_f32_e32 v6, v20, v159
	v_lshl_add_u64 v[4:5], v[4:5], 0, v[72:73]
	global_store_dword v[4:5], v6, off
	v_add_f32_e32 v6, v24, v158
	global_store_dword v[4:5], v6, off offset:64
	v_add_f32_e32 v6, v28, v157
	global_store_dword v[4:5], v6, off offset:128
	v_add_f32_e32 v6, v32, v156
	global_store_dword v[4:5], v6, off offset:192
	v_lshlrev_b64 v[4:5], 12, v[96:97]
	v_lshl_add_u64 v[4:5], s[4:5], 0, v[4:5]
	v_add_f32_e32 v6, v21, v163
	v_lshl_add_u64 v[4:5], v[4:5], 0, v[72:73]
	global_store_dword v[4:5], v6, off
	v_add_f32_e32 v6, v25, v162
	global_store_dword v[4:5], v6, off offset:64
	v_add_f32_e32 v6, v29, v161
	global_store_dword v[4:5], v6, off offset:128
	v_add_f32_e32 v6, v33, v160
	global_store_dword v[4:5], v6, off offset:192
	v_lshlrev_b64 v[4:5], 12, v[98:99]
	v_lshl_add_u64 v[4:5], s[4:5], 0, v[4:5]
	v_add_f32_e32 v6, v22, v170
	v_lshl_add_u64 v[4:5], v[4:5], 0, v[72:73]
	global_store_dword v[4:5], v6, off
	v_add_f32_e32 v6, v26, v169
	global_store_dword v[4:5], v6, off offset:64
	v_add_f32_e32 v6, v30, v168
	global_store_dword v[4:5], v6, off offset:128
	v_add_f32_e32 v6, v34, v165
	global_store_dword v[4:5], v6, off offset:192
	v_lshlrev_b64 v[4:5], 12, v[100:101]
	v_lshl_add_u64 v[4:5], s[4:5], 0, v[4:5]
	s_waitcnt vmcnt(62)
	v_add_f32_e32 v6, v23, v68
	v_lshl_add_u64 v[4:5], v[4:5], 0, v[72:73]
	global_store_dword v[4:5], v6, off
	v_add_f32_e32 v6, v27, v69
	v_readlane_b32 s4, v254, 40
	global_store_dword v[4:5], v6, off offset:64
	s_waitcnt vmcnt(62)
	v_add_f32_e32 v6, v31, v70
	s_add_i32 s17, s17, s4
	global_store_dword v[4:5], v6, off offset:128
	v_add_f32_e32 v6, v35, v58
	s_cmpk_lt_u32 s17, 0x90
	global_store_dword v[4:5], v6, off offset:192
	s_cbranch_scc0 .LBB0_1867
; DI void zero_acc(f32x4 (&acc)[4][4]) {
; #pragma unroll
;   for (int i = 0; i < 4; i++)
; #pragma unroll
;     for (int j = 0; j < 4; j++) acc[i][j] = (f32x4){0.f, 0.f, 0.f, 0.f};
; }
; DI void out_phase(const Params& p, int l, char* smem, const bool dry = false) {
;     ...
;     int mt, nt;
;     if (!xcd_tile(e, 8, mt, nt)) break;
;     f32x4 acc[4][4];
;     zero_acc(acc);
;     gemm_kloop(p.merged + (size_t)mt * 128 * DM, DM, p.Wout + ((size_t)l * DM + nt * 128) * DM, DM, DM, sm, acc);
.LBB0_1738:
	v_mov_b64_e32 v[226:227], s[58:59]
	v_mov_b64_e32 v[228:229], s[86:87]
	v_mov_b64_e32 v[230:231], s[0:1]
	global_load_dwordx2 v[220:221], v[226:227], off
	global_load_dwordx2 v[222:223], v[228:229], off
	global_load_dwordx2 v[224:225], v[230:231], off
	s_cmpk_lt_u32 s17, 0x48
	s_cselect_b32 s4, 0, 0xffffffb8
	s_cselect_b32 s5, 0, 9
	s_add_i32 s19, s4, s17
	s_mul_i32 s4, s19, 0xe39
	s_lshr_b32 s10, s4, 31
	s_ashr_i32 s4, s4, 18
	s_add_i32 s20, s4, s10
	s_mul_i32 s4, s20, 0xffffffb8
	s_add_i32 s12, s4, s19
	s_bfe_u32 s4, s12, 0x3001c
	s_add_i32 s4, s12, s4
	s_sext_i32_i16 s4, s4
	s_ashr_i32 s13, s4, 3
	v_readlane_b32 s4, v254, 19
	s_add_i32 s4, s5, s4
	s_add_i32 s4, s4, s13
	s_ashr_i32 s5, s4, 31
	s_lshl_b64 s[10:11], s[4:5], 18
	v_mov_b32_e32 v7, v182
	s_add_u32 s10, s6, s10
	s_addc_u32 s11, s7, s11
	v_lshlrev_b32_e32 v4, 3, v7
	s_lshl_b32 s5, s20, 10
	s_lshl_b32 s12, s12, 7
	v_ashrrev_i32_e32 v14, 3, v7
	v_and_b32_e32 v15, 56, v4
	s_add_i32 s12, s12, s5
	s_lshl_b32 s5, s13, 10
	v_lshl_or_b32 v4, v14, 10, v15
	v_mov_b32_e32 v5, v164
	s_sub_i32 s18, s12, s5
	v_lshlrev_b64 v[102:103], 1, v[4:5]
	s_ashr_i32 s13, s18, 31
	v_lshl_add_u64 v[4:5], s[10:11], 0, v[102:103]
	s_add_u32 s12, s18, s14
	v_add_co_u32_e32 v8, vcc, s85, v4
	s_addc_u32 s13, s13, 0
	s_nop 0
	v_addc_co_u32_e32 v9, vcc, 0, v5, vcc
	s_lshl_b64 s[12:13], s[12:13], 11
	v_add_co_u32_e32 v10, vcc, s88, v4
	s_add_u32 s12, s8, s12
	s_nop 0
	v_addc_co_u32_e32 v11, vcc, 0, v5, vcc
	s_addc_u32 s13, s9, s13
	v_add_co_u32_e32 v12, vcc, s89, v4
	v_lshl_add_u64 v[20:21], s[12:13], 0, v[102:103]
	s_nop 0
	v_addc_co_u32_e32 v13, vcc, 0, v5, vcc
	v_add_co_u32_e32 v22, vcc, s85, v20
	v_and_b32_e32 v16, 15, v7
	s_nop 0
	v_addc_co_u32_e32 v23, vcc, 0, v21, vcc
	v_add_co_u32_e32 v24, vcc, s88, v20
	v_lshrrev_b32_e32 v17, 1, v7
	s_nop 0
	v_addc_co_u32_e32 v25, vcc, 0, v21, vcc
	v_and_b32_e32 v6, 48, v7
	v_and_b32_e32 v7, 0x4f, v7
	s_mov_b32 s12, 0xfffffc0
	v_add_co_u32_e32 v32, vcc, s89, v20
	v_and_or_b32 v16, v17, s12, v16
	v_mul_u32_u24_e32 v7, 0x48, v7
	v_addc_co_u32_e32 v33, vcc, 0, v21, vcc
	v_mul_lo_u32 v14, v14, s54
	v_mad_u64_u32 v[100:101], s[12:13], v16, s54, v[6:7]
	s_barrier
	global_load_dwordx4 v[36:39], v[4:5], off
	global_load_dwordx4 v[40:43], v[8:9], off
	global_load_dwordx4 v[44:47], v[10:11], off
	global_load_dwordx4 v[48:51], v[12:13], off
	global_load_dwordx4 v[52:55], v[20:21], off
	global_load_dwordx4 v[56:59], v[22:23], off
	global_load_dwordx4 v[60:63], v[24:25], off
	global_load_dwordx4 v[64:67], v[32:33], off
	v_lshl_add_u32 v104, v15, 1, v14
	v_lshl_add_u32 v101, v7, 1, v6
	global_load_dwordx4 v[4:7], v[4:5], off offset:128
	s_nop 0
	global_load_dwordx4 v[16:19], v[8:9], off offset:128
	s_nop 0
	global_load_dwordx4 v[8:11], v[10:11], off offset:128
	s_nop 0
	global_load_dwordx4 v[12:15], v[12:13], off offset:128
	s_nop 0
	global_load_dwordx4 v[28:31], v[20:21], off offset:128
	s_nop 0
	global_load_dwordx4 v[20:23], v[22:23], off offset:128
	s_nop 0
	global_load_dwordx4 v[24:27], v[24:25], off offset:128
	s_nop 0
	global_load_dwordx4 v[32:35], v[32:33], off offset:128
	s_lshl_b32 s12, s19, 7
	s_sub_i32 s5, s12, s5
	s_lshl_b32 s12, s20, 13
	s_sub_i32 s12, s5, s12
	s_ashr_i32 s13, s12, 31
	s_lshl_b64 s[12:13], s[12:13], 11
	s_add_u32 s12, s15, s12
	v_add_u32_e32 v105, 0x9000, v104
	s_addc_u32 s13, s16, s13
	s_mov_b32 s5, -2
	s_waitcnt vmcnt(15)
	ds_write_b128 v104, v[36:39]
	s_waitcnt vmcnt(14)
	ds_write_b128 v104, v[40:43] offset:4608
	s_waitcnt vmcnt(13)
	ds_write_b128 v104, v[44:47] offset:9216
	s_waitcnt vmcnt(12)
	ds_write_b128 v104, v[48:51] offset:13824
	s_waitcnt vmcnt(11)
	ds_write_b128 v104, v[52:55] offset:18432
	s_waitcnt vmcnt(10)
	ds_write_b128 v104, v[56:59] offset:23040
	s_waitcnt vmcnt(9)
	ds_write_b128 v104, v[60:63] offset:27648
	s_waitcnt vmcnt(8)
	ds_write_b128 v104, v[64:67] offset:32256
	v_mov_b32_e32 v36, 0
	v_mov_b32_e32 v37, v36
	v_mov_b32_e32 v38, v36
	v_mov_b32_e32 v39, v36
	v_mov_b32_e32 v92, v36
	v_mov_b32_e32 v93, v36
	v_mov_b32_e32 v94, v36
	v_mov_b32_e32 v95, v36
	v_mov_b32_e32 v40, v36
	v_mov_b32_e32 v41, v36
	v_mov_b32_e32 v42, v36
	v_mov_b32_e32 v43, v36
	v_mov_b32_e32 v44, v36
	v_mov_b32_e32 v45, v36
	v_mov_b32_e32 v46, v36
	v_mov_b32_e32 v47, v36
	v_mov_b32_e32 v48, v36
	v_mov_b32_e32 v49, v36
	v_mov_b32_e32 v50, v36
	v_mov_b32_e32 v51, v36
	v_mov_b32_e32 v52, v36
	v_mov_b32_e32 v53, v36
	v_mov_b32_e32 v54, v36
	v_mov_b32_e32 v55, v36
	v_mov_b32_e32 v56, v36
	v_mov_b32_e32 v57, v36
	v_mov_b32_e32 v58, v36
	v_mov_b32_e32 v59, v36
	v_mov_b32_e32 v60, v36
	v_mov_b32_e32 v61, v36
	v_mov_b32_e32 v62, v36
	v_mov_b32_e32 v63, v36
	v_mov_b32_e32 v64, v36
	v_mov_b32_e32 v65, v36
	v_mov_b32_e32 v66, v36
	v_mov_b32_e32 v67, v36
	v_mov_b32_e32 v68, v36
	v_mov_b32_e32 v69, v36
	v_mov_b32_e32 v70, v36
	v_mov_b32_e32 v71, v36
	v_mov_b32_e32 v72, v36
	v_mov_b32_e32 v73, v36
	v_mov_b32_e32 v74, v36
	v_mov_b32_e32 v75, v36
	v_mov_b32_e32 v76, v36
	v_mov_b32_e32 v77, v36
	v_mov_b32_e32 v78, v36
	v_mov_b32_e32 v79, v36
	v_mov_b32_e32 v80, v36
	v_mov_b32_e32 v81, v36
	v_mov_b32_e32 v82, v36
	v_mov_b32_e32 v83, v36
	v_mov_b32_e32 v84, v36
	v_mov_b32_e32 v85, v36
	v_mov_b32_e32 v86, v36
	v_mov_b32_e32 v87, v36
	v_mov_b32_e32 v88, v36
	v_mov_b32_e32 v89, v36
	v_mov_b32_e32 v90, v36
	v_mov_b32_e32 v91, v36
	v_mov_b32_e32 v96, v36
	v_mov_b32_e32 v97, v36
	v_mov_b32_e32 v98, v36
	v_mov_b32_e32 v99, v36
	s_waitcnt lgkmcnt(0)
	s_barrier

; DI const float* xrow_ptr(const Params& p, int l, int tok) {
;   if (l == 0) return tok < TP ? p.x_prompt + (size_t)tok * DM : p.x_sample + (size_t)(tok - TP) * DM;
;   return p.out + (size_t)tok * DM;
; DI void out_phase(const Params& p, int l, char* smem, const bool dry = false) {
;     ...
; #pragma unroll
;       for (int r = 0; r < 4; r++) {
;         const int tok = mt * 128 + wm * 64 + i * 16 + g4 * 4 + r;
;         const float* xr = xrow_ptr(p, l, tok);
; #pragma unroll
;         for (int jn = 0; jn < 4; jn++) xo[i][r][jn] = xr[nt * 128 + wn * 64 + jn * 16 + cl];
.LBB0_1748:
	s_waitcnt vmcnt(0)
	v_cmp_eq_u32_e64 s[98:99], s58, v72
	v_cmp_eq_u32_e64 s[100:101], s86, v72
	s_nop 1
	v_cndmask_b32_e64 v74, v224, v222, s[100:101]
	v_cndmask_b32_e64 v75, v225, v223, s[100:101]
	v_cndmask_b32_e64 v74, v74, v220, s[98:99]
	v_cndmask_b32_e64 v75, v75, v221, s[98:99]
	v_or_b32_e32 v72, s18, v107
	v_lshlrev_b64 v[70:71], 12, v[70:71]
	v_ashrrev_i32_e32 v73, 31, v72
	v_readlane_b32 s12, v254, 53
	v_readlane_b32 s13, v254, 54
	s_mov_b64 s[10:11], -1
	s_andn2_b64 vcc, exec, s[12:13]
	v_lshl_add_u64 v[70:71], v[74:75], 0, v[70:71]
	v_lshl_add_u64 v[70:71], v[72:73], 2, v[70:71]
	global_load_dword v111, v[70:71], off
	global_load_dword v110, v[70:71], off offset:64
	global_load_dword v109, v[70:71], off offset:128
	global_load_dword v108, v[70:71], off offset:192
	v_or_b32_e32 v70, 1, v68
	v_cndmask_b32_e64 v71, 0, 1, s[12:13]
	v_cmp_ne_u32_e64 s[4:5], 1, v71
	v_ashrrev_i32_e32 v71, 31, v70
	s_cbranch_vccnz .LBB0_1750
	s_mov_b64 s[10:11], 0
	v_mov_b64_e32 v[74:75], v[70:71]

; DI const float* xrow_ptr(const Params& p, int l, int tok) {
;   if (l == 0) return tok < TP ? p.x_prompt + (size_t)tok * DM : p.x_sample + (size_t)(tok - TP) * DM;
;   return p.out + (size_t)tok * DM;
; DI void out_phase(const Params& p, int l, char* smem, const bool dry = false) {
;     ...
; #pragma unroll
;       for (int r = 0; r < 4; r++) {
;         const int tok = mt * 128 + wm * 64 + i * 16 + g4 * 4 + r;
;         const float* xr = xrow_ptr(p, l, tok);
; #pragma unroll
;         for (int jn = 0; jn < 4; jn++) xo[i][r][jn] = xr[nt * 128 + wn * 64 + jn * 16 + cl];
.LBB0_1756:
	v_cmp_eq_u32_e64 s[98:99], s58, v76
	v_cmp_eq_u32_e64 s[100:101], s86, v76
	s_nop 1
	v_cndmask_b32_e64 v76, v224, v222, s[100:101]
	v_cndmask_b32_e64 v77, v225, v223, s[100:101]
	v_cndmask_b32_e64 v76, v76, v220, s[98:99]
	v_cndmask_b32_e64 v77, v77, v221, s[98:99]
	v_lshlrev_b64 v[74:75], 12, v[74:75]
	s_mov_b64 s[10:11], -1
	s_and_b64 vcc, exec, s[4:5]
	v_lshl_add_u64 v[74:75], v[76:77], 0, v[74:75]
	v_lshl_add_u64 v[74:75], v[72:73], 2, v[74:75]
	global_load_dword v115, v[74:75], off
	global_load_dword v114, v[74:75], off offset:64
	global_load_dword v113, v[74:75], off offset:128
	global_load_dword v112, v[74:75], off offset:192
	v_or_b32_e32 v74, 2, v68
	v_ashrrev_i32_e32 v75, 31, v74
	s_cbranch_vccnz .LBB0_1758
	s_mov_b64 s[10:11], 0
	v_mov_b64_e32 v[76:77], v[74:75]

; DI const float* xrow_ptr(const Params& p, int l, int tok) {
;   if (l == 0) return tok < TP ? p.x_prompt + (size_t)tok * DM : p.x_sample + (size_t)(tok - TP) * DM;
;   return p.out + (size_t)tok * DM;
; DI void out_phase(const Params& p, int l, char* smem, const bool dry = false) {
;     ...
; #pragma unroll
;       for (int r = 0; r < 4; r++) {
;         const int tok = mt * 128 + wm * 64 + i * 16 + g4 * 4 + r;
;         const float* xr = xrow_ptr(p, l, tok);
; #pragma unroll
;         for (int jn = 0; jn < 4; jn++) xo[i][r][jn] = xr[nt * 128 + wn * 64 + jn * 16 + cl];
.LBB0_1764:
	v_cmp_eq_u32_e64 s[98:99], s58, v78
	v_cmp_eq_u32_e64 s[100:101], s86, v78
	s_nop 1
	v_cndmask_b32_e64 v78, v224, v222, s[100:101]
	v_cndmask_b32_e64 v79, v225, v223, s[100:101]
	v_cndmask_b32_e64 v78, v78, v220, s[98:99]
	v_cndmask_b32_e64 v79, v79, v221, s[98:99]
	v_lshlrev_b64 v[76:77], 12, v[76:77]
	s_mov_b64 s[10:11], -1
	s_and_b64 vcc, exec, s[4:5]
	v_lshl_add_u64 v[76:77], v[78:79], 0, v[76:77]
	v_lshl_add_u64 v[76:77], v[72:73], 2, v[76:77]
	global_load_dword v119, v[76:77], off
	global_load_dword v118, v[76:77], off offset:64
	global_load_dword v117, v[76:77], off offset:128
	global_load_dword v116, v[76:77], off offset:192
	v_or_b32_e32 v76, 3, v68
	v_ashrrev_i32_e32 v77, 31, v76
	s_cbranch_vccnz .LBB0_1766
	s_mov_b64 s[10:11], 0
	v_mov_b64_e32 v[78:79], v[76:77]

; DI const float* xrow_ptr(const Params& p, int l, int tok) {
;   if (l == 0) return tok < TP ? p.x_prompt + (size_t)tok * DM : p.x_sample + (size_t)(tok - TP) * DM;
;   return p.out + (size_t)tok * DM;
; DI void out_phase(const Params& p, int l, char* smem, const bool dry = false) {
;     ...
; #pragma unroll
;       for (int r = 0; r < 4; r++) {
;         const int tok = mt * 128 + wm * 64 + i * 16 + g4 * 4 + r;
;         const float* xr = xrow_ptr(p, l, tok);
; #pragma unroll
;         for (int jn = 0; jn < 4; jn++) xo[i][r][jn] = xr[nt * 128 + wn * 64 + jn * 16 + cl];
.LBB0_1772:
	v_cmp_eq_u32_e64 s[98:99], s58, v80
	v_cmp_eq_u32_e64 s[100:101], s86, v80
	s_nop 1
	v_cndmask_b32_e64 v80, v224, v222, s[100:101]
	v_cndmask_b32_e64 v81, v225, v223, s[100:101]
	v_cndmask_b32_e64 v80, v80, v220, s[98:99]
	v_cndmask_b32_e64 v81, v81, v221, s[98:99]
	v_lshlrev_b64 v[78:79], 12, v[78:79]
	s_mov_b64 s[10:11], -1
	s_and_b64 vcc, exec, s[4:5]
	v_lshl_add_u64 v[78:79], v[80:81], 0, v[78:79]
	v_lshl_add_u64 v[78:79], v[72:73], 2, v[78:79]
	global_load_dword v123, v[78:79], off
	global_load_dword v122, v[78:79], off offset:64
	global_load_dword v121, v[78:79], off offset:128
	global_load_dword v120, v[78:79], off offset:192
	v_or_b32_e32 v78, 16, v68
	v_ashrrev_i32_e32 v79, 31, v78
	s_cbranch_vccnz .LBB0_1774
	s_mov_b64 s[10:11], 0
	v_mov_b64_e32 v[80:81], v[78:79]

; DI const float* xrow_ptr(const Params& p, int l, int tok) {
;   if (l == 0) return tok < TP ? p.x_prompt + (size_t)tok * DM : p.x_sample + (size_t)(tok - TP) * DM;
;   return p.out + (size_t)tok * DM;
; DI void out_phase(const Params& p, int l, char* smem, const bool dry = false) {
;     ...
; #pragma unroll
;       for (int r = 0; r < 4; r++) {
;         const int tok = mt * 128 + wm * 64 + i * 16 + g4 * 4 + r;
;         const float* xr = xrow_ptr(p, l, tok);
; #pragma unroll
;         for (int jn = 0; jn < 4; jn++) xo[i][r][jn] = xr[nt * 128 + wn * 64 + jn * 16 + cl];
.LBB0_1780:
	v_cmp_eq_u32_e64 s[98:99], s58, v82
	v_cmp_eq_u32_e64 s[100:101], s86, v82
	s_nop 1
	v_cndmask_b32_e64 v82, v224, v222, s[100:101]
	v_cndmask_b32_e64 v83, v225, v223, s[100:101]
	v_cndmask_b32_e64 v82, v82, v220, s[98:99]
	v_cndmask_b32_e64 v83, v83, v221, s[98:99]
	v_lshlrev_b64 v[80:81], 12, v[80:81]
	s_mov_b64 s[10:11], -1
	s_and_b64 vcc, exec, s[4:5]
	v_lshl_add_u64 v[80:81], v[82:83], 0, v[80:81]
	v_lshl_add_u64 v[80:81], v[72:73], 2, v[80:81]
	global_load_dword v127, v[80:81], off
	global_load_dword v126, v[80:81], off offset:64
	global_load_dword v125, v[80:81], off offset:128
	global_load_dword v124, v[80:81], off offset:192
	v_or_b32_e32 v80, 17, v68
	v_ashrrev_i32_e32 v81, 31, v80
	s_cbranch_vccnz .LBB0_1782
	s_mov_b64 s[10:11], 0
	v_mov_b64_e32 v[82:83], v[80:81]

; DI const float* xrow_ptr(const Params& p, int l, int tok) {
;   if (l == 0) return tok < TP ? p.x_prompt + (size_t)tok * DM : p.x_sample + (size_t)(tok - TP) * DM;
;   return p.out + (size_t)tok * DM;
; DI void out_phase(const Params& p, int l, char* smem, const bool dry = false) {
;     ...
; #pragma unroll
;       for (int r = 0; r < 4; r++) {
;         const int tok = mt * 128 + wm * 64 + i * 16 + g4 * 4 + r;
;         const float* xr = xrow_ptr(p, l, tok);
; #pragma unroll
;         for (int jn = 0; jn < 4; jn++) xo[i][r][jn] = xr[nt * 128 + wn * 64 + jn * 16 + cl];
.LBB0_1788:
	v_cmp_eq_u32_e64 s[98:99], s58, v84
	v_cmp_eq_u32_e64 s[100:101], s86, v84
	s_nop 1
	v_cndmask_b32_e64 v84, v224, v222, s[100:101]
	v_cndmask_b32_e64 v85, v225, v223, s[100:101]
	v_cndmask_b32_e64 v84, v84, v220, s[98:99]
	v_cndmask_b32_e64 v85, v85, v221, s[98:99]
	v_lshlrev_b64 v[82:83], 12, v[82:83]
	s_mov_b64 s[10:11], -1
	s_and_b64 vcc, exec, s[4:5]
	v_lshl_add_u64 v[82:83], v[84:85], 0, v[82:83]
	v_lshl_add_u64 v[82:83], v[72:73], 2, v[82:83]
	global_load_dword v131, v[82:83], off
	global_load_dword v130, v[82:83], off offset:64
	global_load_dword v129, v[82:83], off offset:128
	global_load_dword v128, v[82:83], off offset:192
	v_or_b32_e32 v82, 18, v68
	v_ashrrev_i32_e32 v83, 31, v82
	s_cbranch_vccnz .LBB0_1790
	s_mov_b64 s[10:11], 0
	v_mov_b64_e32 v[84:85], v[82:83]

; DI const float* xrow_ptr(const Params& p, int l, int tok) {
;   if (l == 0) return tok < TP ? p.x_prompt + (size_t)tok * DM : p.x_sample + (size_t)(tok - TP) * DM;
;   return p.out + (size_t)tok * DM;
; DI void out_phase(const Params& p, int l, char* smem, const bool dry = false) {
;     ...
; #pragma unroll
;       for (int r = 0; r < 4; r++) {
;         const int tok = mt * 128 + wm * 64 + i * 16 + g4 * 4 + r;
;         const float* xr = xrow_ptr(p, l, tok);
; #pragma unroll
;         for (int jn = 0; jn < 4; jn++) xo[i][r][jn] = xr[nt * 128 + wn * 64 + jn * 16 + cl];
.LBB0_1796:
	v_cmp_eq_u32_e64 s[98:99], s58, v86
	v_cmp_eq_u32_e64 s[100:101], s86, v86
	s_nop 1
	v_cndmask_b32_e64 v86, v224, v222, s[100:101]
	v_cndmask_b32_e64 v87, v225, v223, s[100:101]
	v_cndmask_b32_e64 v86, v86, v220, s[98:99]
	v_cndmask_b32_e64 v87, v87, v221, s[98:99]
	v_lshlrev_b64 v[84:85], 12, v[84:85]
	s_mov_b64 s[10:11], -1
	s_and_b64 vcc, exec, s[4:5]
	v_lshl_add_u64 v[84:85], v[86:87], 0, v[84:85]
	v_lshl_add_u64 v[84:85], v[72:73], 2, v[84:85]
	global_load_dword v135, v[84:85], off
	global_load_dword v134, v[84:85], off offset:64
	global_load_dword v133, v[84:85], off offset:128
	global_load_dword v132, v[84:85], off offset:192
	v_or_b32_e32 v84, 19, v68
	v_ashrrev_i32_e32 v85, 31, v84
	s_cbranch_vccnz .LBB0_1798
	s_mov_b64 s[10:11], 0
	v_mov_b64_e32 v[86:87], v[84:85]

; DI const float* xrow_ptr(const Params& p, int l, int tok) {
;   if (l == 0) return tok < TP ? p.x_prompt + (size_t)tok * DM : p.x_sample + (size_t)(tok - TP) * DM;
;   return p.out + (size_t)tok * DM;
; DI void out_phase(const Params& p, int l, char* smem, const bool dry = false) {
;     ...
; #pragma unroll
;       for (int r = 0; r < 4; r++) {
;         const int tok = mt * 128 + wm * 64 + i * 16 + g4 * 4 + r;
;         const float* xr = xrow_ptr(p, l, tok);
; #pragma unroll
;         for (int jn = 0; jn < 4; jn++) xo[i][r][jn] = xr[nt * 128 + wn * 64 + jn * 16 + cl];
.LBB0_1804:
	v_cmp_eq_u32_e64 s[98:99], s58, v88
	v_cmp_eq_u32_e64 s[100:101], s86, v88
	s_nop 1
	v_cndmask_b32_e64 v88, v224, v222, s[100:101]
	v_cndmask_b32_e64 v89, v225, v223, s[100:101]
	v_cndmask_b32_e64 v88, v88, v220, s[98:99]
	v_cndmask_b32_e64 v89, v89, v221, s[98:99]
	v_lshlrev_b64 v[86:87], 12, v[86:87]
	s_mov_b64 s[10:11], -1
	s_and_b64 vcc, exec, s[4:5]
	v_lshl_add_u64 v[86:87], v[88:89], 0, v[86:87]
	v_lshl_add_u64 v[86:87], v[72:73], 2, v[86:87]
	global_load_dword v139, v[86:87], off
	global_load_dword v138, v[86:87], off offset:64
	global_load_dword v137, v[86:87], off offset:128
	global_load_dword v136, v[86:87], off offset:192
	v_or_b32_e32 v86, 32, v68
	v_ashrrev_i32_e32 v87, 31, v86
	s_cbranch_vccnz .LBB0_1806
	s_mov_b64 s[10:11], 0
	v_mov_b64_e32 v[88:89], v[86:87]

; DI const float* xrow_ptr(const Params& p, int l, int tok) {
;   if (l == 0) return tok < TP ? p.x_prompt + (size_t)tok * DM : p.x_sample + (size_t)(tok - TP) * DM;
;   return p.out + (size_t)tok * DM;
; DI void out_phase(const Params& p, int l, char* smem, const bool dry = false) {
;     ...
; #pragma unroll
;       for (int r = 0; r < 4; r++) {
;         const int tok = mt * 128 + wm * 64 + i * 16 + g4 * 4 + r;
;         const float* xr = xrow_ptr(p, l, tok);
; #pragma unroll
;         for (int jn = 0; jn < 4; jn++) xo[i][r][jn] = xr[nt * 128 + wn * 64 + jn * 16 + cl];
.LBB0_1812:
	v_cmp_eq_u32_e64 s[98:99], s58, v90
	v_cmp_eq_u32_e64 s[100:101], s86, v90
	s_nop 1
	v_cndmask_b32_e64 v90, v224, v222, s[100:101]
	v_cndmask_b32_e64 v91, v225, v223, s[100:101]
	v_cndmask_b32_e64 v90, v90, v220, s[98:99]
	v_cndmask_b32_e64 v91, v91, v221, s[98:99]
	v_lshlrev_b64 v[88:89], 12, v[88:89]
	s_mov_b64 s[10:11], -1
	s_and_b64 vcc, exec, s[4:5]
	v_lshl_add_u64 v[88:89], v[90:91], 0, v[88:89]
	v_lshl_add_u64 v[88:89], v[72:73], 2, v[88:89]
	global_load_dword v143, v[88:89], off
	global_load_dword v142, v[88:89], off offset:64
	global_load_dword v141, v[88:89], off offset:128
	global_load_dword v140, v[88:89], off offset:192
	v_or_b32_e32 v88, 33, v68
	v_ashrrev_i32_e32 v89, 31, v88
	s_cbranch_vccnz .LBB0_1814
	s_mov_b64 s[10:11], 0
	v_mov_b64_e32 v[90:91], v[88:89]

; DI const float* xrow_ptr(const Params& p, int l, int tok) {
;   if (l == 0) return tok < TP ? p.x_prompt + (size_t)tok * DM : p.x_sample + (size_t)(tok - TP) * DM;
;   return p.out + (size_t)tok * DM;
; DI void out_phase(const Params& p, int l, char* smem, const bool dry = false) {
;     ...
; #pragma unroll
;       for (int r = 0; r < 4; r++) {
;         const int tok = mt * 128 + wm * 64 + i * 16 + g4 * 4 + r;
;         const float* xr = xrow_ptr(p, l, tok);
; #pragma unroll
;         for (int jn = 0; jn < 4; jn++) xo[i][r][jn] = xr[nt * 128 + wn * 64 + jn * 16 + cl];
.LBB0_1820:
	v_cmp_eq_u32_e64 s[98:99], s58, v92
	v_cmp_eq_u32_e64 s[100:101], s86, v92
	s_nop 1
	v_cndmask_b32_e64 v92, v224, v222, s[100:101]
	v_cndmask_b32_e64 v93, v225, v223, s[100:101]
	v_cndmask_b32_e64 v92, v92, v220, s[98:99]
	v_cndmask_b32_e64 v93, v93, v221, s[98:99]
	v_lshlrev_b64 v[90:91], 12, v[90:91]
	s_mov_b64 s[10:11], -1
	s_and_b64 vcc, exec, s[4:5]
	v_lshl_add_u64 v[90:91], v[92:93], 0, v[90:91]
	v_lshl_add_u64 v[90:91], v[72:73], 2, v[90:91]
	global_load_dword v147, v[90:91], off
	global_load_dword v146, v[90:91], off offset:64
	global_load_dword v145, v[90:91], off offset:128
	global_load_dword v144, v[90:91], off offset:192
	v_or_b32_e32 v90, 34, v68
	v_ashrrev_i32_e32 v91, 31, v90
	s_cbranch_vccnz .LBB0_1822
	s_mov_b64 s[10:11], 0
	v_mov_b64_e32 v[92:93], v[90:91]

; DI const float* xrow_ptr(const Params& p, int l, int tok) {
;   if (l == 0) return tok < TP ? p.x_prompt + (size_t)tok * DM : p.x_sample + (size_t)(tok - TP) * DM;
;   return p.out + (size_t)tok * DM;
; DI void out_phase(const Params& p, int l, char* smem, const bool dry = false) {
;     ...
; #pragma unroll
;       for (int r = 0; r < 4; r++) {
;         const int tok = mt * 128 + wm * 64 + i * 16 + g4 * 4 + r;
;         const float* xr = xrow_ptr(p, l, tok);
; #pragma unroll
;         for (int jn = 0; jn < 4; jn++) xo[i][r][jn] = xr[nt * 128 + wn * 64 + jn * 16 + cl];
.LBB0_1828:
	v_cmp_eq_u32_e64 s[98:99], s58, v94
	v_cmp_eq_u32_e64 s[100:101], s86, v94
	s_nop 1
	v_cndmask_b32_e64 v94, v224, v222, s[100:101]
	v_cndmask_b32_e64 v95, v225, v223, s[100:101]
	v_cndmask_b32_e64 v94, v94, v220, s[98:99]
	v_cndmask_b32_e64 v95, v95, v221, s[98:99]
	v_lshlrev_b64 v[92:93], 12, v[92:93]
	s_mov_b64 s[10:11], -1
	s_and_b64 vcc, exec, s[4:5]
	v_lshl_add_u64 v[92:93], v[94:95], 0, v[92:93]
	v_lshl_add_u64 v[92:93], v[72:73], 2, v[92:93]
	global_load_dword v151, v[92:93], off
	global_load_dword v150, v[92:93], off offset:64
	global_load_dword v149, v[92:93], off offset:128
	global_load_dword v148, v[92:93], off offset:192
	v_or_b32_e32 v92, 35, v68
	v_ashrrev_i32_e32 v93, 31, v92
	s_cbranch_vccnz .LBB0_1830
	s_mov_b64 s[10:11], 0
	v_mov_b64_e32 v[94:95], v[92:93]

; DI const float* xrow_ptr(const Params& p, int l, int tok) {
;   if (l == 0) return tok < TP ? p.x_prompt + (size_t)tok * DM : p.x_sample + (size_t)(tok - TP) * DM;
;   return p.out + (size_t)tok * DM;
; DI void out_phase(const Params& p, int l, char* smem, const bool dry = false) {
;     ...
; #pragma unroll
;       for (int r = 0; r < 4; r++) {
;         const int tok = mt * 128 + wm * 64 + i * 16 + g4 * 4 + r;
;         const float* xr = xrow_ptr(p, l, tok);
; #pragma unroll
;         for (int jn = 0; jn < 4; jn++) xo[i][r][jn] = xr[nt * 128 + wn * 64 + jn * 16 + cl];
.LBB0_1836:
	v_cmp_eq_u32_e64 s[98:99], s58, v96
	v_cmp_eq_u32_e64 s[100:101], s86, v96
	s_nop 1
	v_cndmask_b32_e64 v96, v224, v222, s[100:101]
	v_cndmask_b32_e64 v97, v225, v223, s[100:101]
	v_cndmask_b32_e64 v96, v96, v220, s[98:99]
	v_cndmask_b32_e64 v97, v97, v221, s[98:99]
	v_lshlrev_b64 v[94:95], 12, v[94:95]
	s_mov_b64 s[10:11], -1
	s_and_b64 vcc, exec, s[4:5]
	v_lshl_add_u64 v[94:95], v[96:97], 0, v[94:95]
	v_lshl_add_u64 v[94:95], v[72:73], 2, v[94:95]
	global_load_dword v155, v[94:95], off
	global_load_dword v154, v[94:95], off offset:64
	global_load_dword v153, v[94:95], off offset:128
	global_load_dword v152, v[94:95], off offset:192
	v_or_b32_e32 v94, 48, v68
	v_ashrrev_i32_e32 v95, 31, v94
	s_cbranch_vccnz .LBB0_1838
	s_mov_b64 s[10:11], 0
	v_mov_b64_e32 v[96:97], v[94:95]

; DI const float* xrow_ptr(const Params& p, int l, int tok) {
;   if (l == 0) return tok < TP ? p.x_prompt + (size_t)tok * DM : p.x_sample + (size_t)(tok - TP) * DM;
;   return p.out + (size_t)tok * DM;
; DI void out_phase(const Params& p, int l, char* smem, const bool dry = false) {
;     ...
; #pragma unroll
;       for (int r = 0; r < 4; r++) {
;         const int tok = mt * 128 + wm * 64 + i * 16 + g4 * 4 + r;
;         const float* xr = xrow_ptr(p, l, tok);
; #pragma unroll
;         for (int jn = 0; jn < 4; jn++) xo[i][r][jn] = xr[nt * 128 + wn * 64 + jn * 16 + cl];
.LBB0_1844:
	v_cmp_eq_u32_e64 s[98:99], s58, v98
	v_cmp_eq_u32_e64 s[100:101], s86, v98
	s_nop 1
	v_cndmask_b32_e64 v98, v224, v222, s[100:101]
	v_cndmask_b32_e64 v99, v225, v223, s[100:101]
	v_cndmask_b32_e64 v98, v98, v220, s[98:99]
	v_cndmask_b32_e64 v99, v99, v221, s[98:99]
	v_lshlrev_b64 v[96:97], 12, v[96:97]
	s_mov_b64 s[10:11], -1
	s_and_b64 vcc, exec, s[4:5]
	v_lshl_add_u64 v[96:97], v[98:99], 0, v[96:97]
	v_lshl_add_u64 v[96:97], v[72:73], 2, v[96:97]
	global_load_dword v159, v[96:97], off
	global_load_dword v158, v[96:97], off offset:64
	global_load_dword v157, v[96:97], off offset:128
	global_load_dword v156, v[96:97], off offset:192
	v_or_b32_e32 v96, 49, v68
	v_ashrrev_i32_e32 v97, 31, v96
	s_cbranch_vccnz .LBB0_1846
	s_mov_b64 s[10:11], 0
	v_mov_b64_e32 v[98:99], v[96:97]

; DI const float* xrow_ptr(const Params& p, int l, int tok) {
;   if (l == 0) return tok < TP ? p.x_prompt + (size_t)tok * DM : p.x_sample + (size_t)(tok - TP) * DM;
;   return p.out + (size_t)tok * DM;
; DI void out_phase(const Params& p, int l, char* smem, const bool dry = false) {
;     ...
; #pragma unroll
;       for (int r = 0; r < 4; r++) {
;         const int tok = mt * 128 + wm * 64 + i * 16 + g4 * 4 + r;
;         const float* xr = xrow_ptr(p, l, tok);
; #pragma unroll
;         for (int jn = 0; jn < 4; jn++) xo[i][r][jn] = xr[nt * 128 + wn * 64 + jn * 16 + cl];
.LBB0_1852:
	v_cmp_eq_u32_e64 s[98:99], s58, v100
	v_cmp_eq_u32_e64 s[100:101], s86, v100
	s_nop 1
	v_cndmask_b32_e64 v100, v224, v222, s[100:101]
	v_cndmask_b32_e64 v101, v225, v223, s[100:101]
	v_cndmask_b32_e64 v100, v100, v220, s[98:99]
	v_cndmask_b32_e64 v101, v101, v221, s[98:99]
	v_lshlrev_b64 v[98:99], 12, v[98:99]
	s_mov_b64 s[10:11], -1
	s_and_b64 vcc, exec, s[4:5]
	v_lshl_add_u64 v[98:99], v[100:101], 0, v[98:99]
	v_lshl_add_u64 v[98:99], v[72:73], 2, v[98:99]
	global_load_dword v163, v[98:99], off
	global_load_dword v162, v[98:99], off offset:64
	global_load_dword v161, v[98:99], off offset:128
	global_load_dword v160, v[98:99], off offset:192
	v_or_b32_e32 v98, 50, v68
	v_ashrrev_i32_e32 v99, 31, v98
	s_cbranch_vccnz .LBB0_1854
	s_mov_b64 s[10:11], 0
	v_mov_b64_e32 v[100:101], v[98:99]

; DI const float* xrow_ptr(const Params& p, int l, int tok) {
;   if (l == 0) return tok < TP ? p.x_prompt + (size_t)tok * DM : p.x_sample + (size_t)(tok - TP) * DM;
;   return p.out + (size_t)tok * DM;
; DI void out_phase(const Params& p, int l, char* smem, const bool dry = false) {
;     ...
; #pragma unroll
;       for (int r = 0; r < 4; r++) {
;         const int tok = mt * 128 + wm * 64 + i * 16 + g4 * 4 + r;
;         const float* xr = xrow_ptr(p, l, tok);
; #pragma unroll
;         for (int jn = 0; jn < 4; jn++) xo[i][r][jn] = xr[nt * 128 + wn * 64 + jn * 16 + cl];
.LBB0_1860:
	v_cmp_eq_u32_e64 s[98:99], s58, v102
	v_cmp_eq_u32_e64 s[100:101], s86, v102
	s_nop 1
	v_cndmask_b32_e64 v102, v224, v222, s[100:101]
	v_cndmask_b32_e64 v103, v225, v223, s[100:101]
	v_cndmask_b32_e64 v102, v102, v220, s[98:99]
	v_cndmask_b32_e64 v103, v103, v221, s[98:99]
	v_lshlrev_b64 v[100:101], 12, v[100:101]
	s_and_b64 vcc, exec, s[4:5]
	s_mov_b64 s[4:5], -1
	v_lshl_add_u64 v[100:101], v[102:103], 0, v[100:101]
	v_lshl_add_u64 v[100:101], v[72:73], 2, v[100:101]
	global_load_dword v170, v[100:101], off
	global_load_dword v169, v[100:101], off offset:64
	global_load_dword v168, v[100:101], off offset:128
	global_load_dword v165, v[100:101], off offset:192
	v_or_b32_e32 v100, 51, v68
	s_cbranch_vccnz .LBB0_1862
	v_ashrrev_i32_e32 v101, 31, v100
	s_mov_b64 s[4:5], 0
